# attention steady loop: row sums with packed f32 adds (v_pk_add_f32 into a dead register pair), 17 VALU instead of 35 per half step
# baseline (speedup 1.0000x reference)
.LBB0_77:
	v_add_u32_e32 v0, s44, v233
	ds_read_b64_tr_b16 v[62:63], v0 offset:24576
	ds_read_b64_tr_b16 v[64:65], v0 offset:25088
	v_pk_add_f32 v[208:209], v[82:83], v[84:85]
	v_pk_add_f32 v[208:209], v[86:87], v[208:209]
	v_cvt_pk_f16_f32 v160, v82, v83
	v_cvt_pk_f16_f32 v161, v84, v85
	s_waitcnt lgkmcnt(9)
	v_mfma_f32_32x32x16_f16 v[114:129], v[192:195], v[144:147], v[2:17]
	ds_read_b64_tr_b16 v[82:83], v0 offset:28672
	ds_read_b64_tr_b16 v[84:85], v0 offset:29184
	v_pk_add_f32 v[208:209], v[88:89], v[208:209]
	v_pk_add_f32 v[208:209], v[90:91], v[208:209]
	v_cvt_pk_f16_f32 v162, v86, v87
	v_cvt_pk_f16_f32 v163, v88, v89
	s_waitcnt lgkmcnt(10)
	v_mfma_f32_32x32x16_f16 v[98:113], v[188:191], v[144:147], v[2:17]
	ds_read_b64_tr_b16 v[86:87], v0 offset:25600
	ds_read_b64_tr_b16 v[88:89], v0 offset:26112
	v_pk_add_f32 v[208:209], v[92:93], v[208:209]
	v_pk_add_f32 v[208:209], v[94:95], v[208:209]
	v_cvt_pk_f16_f32 v156, v90, v91
	v_cvt_pk_f16_f32 v157, v92, v93
	s_waitcnt lgkmcnt(11)
	v_mfma_f32_32x32x16_f16 v[114:129], v[184:187], v[140:143], v[114:129]
	ds_read_b64_tr_b16 v[90:91], v0 offset:29696
	ds_read_b64_tr_b16 v[92:93], v0 offset:30208
	v_pk_add_f32 v[208:209], v[96:97], v[208:209]
	v_pk_add_f32 v[208:209], v[66:67], v[208:209]
	v_cvt_pk_f16_f32 v158, v94, v95
	v_cvt_pk_f16_f32 v159, v96, v97
	s_waitcnt lgkmcnt(12)
	v_mfma_f32_32x32x16_f16 v[98:113], v[180:183], v[140:143], v[98:113]
	ds_read_b64_tr_b16 v[94:95], v0 offset:26624
	ds_read_b64_tr_b16 v[96:97], v0 offset:27136
	v_pk_add_f32 v[208:209], v[68:69], v[208:209]
	v_pk_add_f32 v[208:209], v[70:71], v[208:209]
	v_cvt_pk_f16_f32 v152, v66, v67
	v_cvt_pk_f16_f32 v153, v68, v69
	s_waitcnt lgkmcnt(13)
	v_mfma_f32_32x32x16_f16 v[114:129], v[176:179], v[136:139], v[114:129]
	ds_read_b64_tr_b16 v[66:67], v0 offset:30720
	ds_read_b64_tr_b16 v[68:69], v0 offset:31232
	v_pk_add_f32 v[208:209], v[72:73], v[208:209]
	v_pk_add_f32 v[208:209], v[74:75], v[208:209]
	v_cvt_pk_f16_f32 v154, v70, v71
	v_cvt_pk_f16_f32 v155, v72, v73
	s_waitcnt lgkmcnt(14)
	v_mfma_f32_32x32x16_f16 v[98:113], v[172:175], v[136:139], v[98:113]
	ds_read_b64_tr_b16 v[70:71], v0 offset:27648
	ds_read_b64_tr_b16 v[72:73], v0 offset:28160
	v_pk_add_f32 v[208:209], v[76:77], v[208:209]
	v_pk_add_f32 v[208:209], v[78:79], v[208:209]
	v_cvt_pk_f16_f32 v148, v74, v75
	v_cvt_pk_f16_f32 v149, v76, v77
	s_waitcnt lgkmcnt(14)
	v_mfma_f32_32x32x16_f16 v[114:129], v[168:171], v[132:135], v[114:129]
	ds_read_b64_tr_b16 v[74:75], v0 offset:31744
	ds_read_b64_tr_b16 v[76:77], v0 offset:32256
	v_pk_add_f32 v[208:209], v[80:81], v[208:209]
	v_add_f32_e32 v0, v208, v209
	v_cvt_pk_f16_f32 v150, v78, v79
	v_cvt_pk_f16_f32 v151, v80, v81
	v_mfma_f32_32x32x16_f16 v[98:113], v[164:167], v[132:135], v[98:113]
	v_lshl_add_u64 v[58:59], v[56:57], 0, s[2:3]
	v_add_f32_e32 v0, v50, v0
	v_lshl_add_u64 v[50:51], v[58:59], 0, s[46:47]
	s_add_i32 s43, s42, s97
	s_mov_b32 s44, m0
	s_mov_b32 m0, s43
	s_nop 0
	global_load_lds_dwordx4 v[50:51], off
	s_mov_b32 m0, s44
	v_lshl_add_u64 v[60:61], v[54:55], 0, s[2:3]
	v_lshl_add_u64 v[50:51], v[60:61], 0, s[36:37]
	s_add_i32 s43, s25, s83
	s_mov_b32 s44, m0
	s_mov_b32 m0, s43
	s_nop 0
	global_load_lds_dwordx4 v[50:51], off
	s_mov_b32 m0, s44
	s_waitcnt lgkmcnt(14)
	v_mfma_f32_32x32x16_f16 v[18:33], v[160:163], v[62:65], v[18:33]
	v_exp_f32_e32 v114, v114
	v_exp_f32_e32 v115, v115
	v_exp_f32_e32 v116, v116
	v_exp_f32_e32 v117, v117
	s_waitcnt lgkmcnt(12)
	v_mfma_f32_32x32x16_f16 v[34:49], v[160:163], v[82:85], v[34:49]
	v_exp_f32_e32 v118, v118
	v_exp_f32_e32 v119, v119
	v_exp_f32_e32 v120, v120
	v_exp_f32_e32 v121, v121
	v_add_u32_e32 v50, s25, v219
	ds_read_b128 v[62:65], v50
	ds_read_b128 v[164:167], v50 offset:512
	s_waitcnt lgkmcnt(12)
	v_mfma_f32_32x32x16_f16 v[18:33], v[156:159], v[86:89], v[18:33]
	v_exp_f32_e32 v122, v122
	v_exp_f32_e32 v123, v123
	v_exp_f32_e32 v124, v124
	v_exp_f32_e32 v125, v125
	ds_read_b128 v[168:171], v50 offset:2048
	ds_read_b128 v[172:175], v50 offset:2560
	s_waitcnt lgkmcnt(12)
	v_mfma_f32_32x32x16_f16 v[34:49], v[156:159], v[90:93], v[34:49]
	v_exp_f32_e32 v126, v126
	v_exp_f32_e32 v127, v127
	v_exp_f32_e32 v128, v128
	v_exp_f32_e32 v129, v129
	ds_read_b128 v[176:179], v50 offset:4096
	ds_read_b128 v[180:183], v50 offset:4608
	s_waitcnt lgkmcnt(12)
	v_mfma_f32_32x32x16_f16 v[18:33], v[152:155], v[94:97], v[18:33]
	v_exp_f32_e32 v98, v98
	v_exp_f32_e32 v99, v99
	v_exp_f32_e32 v100, v100
	v_exp_f32_e32 v101, v101
	ds_read_b128 v[184:187], v50 offset:6144
	ds_read_b128 v[50:53], v50 offset:6656
	s_waitcnt lgkmcnt(12)
	v_mfma_f32_32x32x16_f16 v[34:49], v[152:155], v[66:69], v[34:49]
	v_exp_f32_e32 v102, v102
	v_exp_f32_e32 v103, v103
	v_exp_f32_e32 v104, v104
	v_exp_f32_e32 v105, v105
	s_waitcnt lgkmcnt(10)
	v_mfma_f32_32x32x16_f16 v[18:33], v[148:151], v[70:73], v[18:33]
	v_exp_f32_e32 v106, v106
	v_exp_f32_e32 v107, v107
	v_exp_f32_e32 v108, v108
	v_exp_f32_e32 v109, v109
	s_waitcnt lgkmcnt(8)
	v_mfma_f32_32x32x16_f16 v[34:49], v[148:151], v[74:77], v[34:49]
	v_exp_f32_e32 v110, v110
	v_exp_f32_e32 v111, v111
	v_exp_f32_e32 v112, v112
	v_exp_f32_e32 v113, v113
	s_waitcnt vmcnt(2) lgkmcnt(8)
	s_barrier
; #define WAIT_BAR(N) asm volatile("s_waitcnt vmcnt(" #N ") lgkmcnt(0)\n\ts_barrier" ::: "memory")
; #define RESC() do { if (!FIXM && resc) { asm volatile("s_waitcnt lgkmcnt(0)" ::: "memory"); \
;       _Pragma("unroll") for (int d_ = 0; d_ < 2; ++d_) _Pragma("unroll") for (int r = 0; r < 16; ++r) o[d_][r] *= wsf[crow(r, hi)]; } } while (0)
; #define ROT() do { sl_prev = sl_cur; sl_cur = sl_next; sl_next = (sl_next == (NSLOT - 1) * SLOTB) ? 0 : sl_next + SLOTB; } while (0)
; template <int THRL, bool FIXM> __device__ __forceinline__ bool attn_unit(const h16* Qrows, const h16* __restrict__ Kh, const h16* __restrict__ Vh, const int NT, h16* Yrows, const h16* BZrows, char* shm, const int tid, const float mfix, ...
;     ...
;   int t = 1;
;   for (; t + 5 < NT; t += 2) {
;     STEP(pB0, pB1, pA0, pA1, t, true, true, true);     WAIT_BAR(2); RESC(); ROT();
;     STEP(pA0, pA1, pB0, pB1, t + 1, true, true, true); WAIT_BAR(2); RESC(); ROT();
	s_add_i32 s43, s25, 0x2000
	s_cmpk_lg_i32 s25, 0x4000
	s_cselect_b32 s43, s43, 0
	v_add_u32_e32 v192, s42, v233
	ds_read_b64_tr_b16 v[188:189], v192 offset:24576
	ds_read_b64_tr_b16 v[190:191], v192 offset:25088
	s_waitcnt lgkmcnt(9)
	v_mfma_f32_32x32x16_f16 v[82:97], v[62:65], v[144:147], v[2:17]
	v_pk_add_f32 v[208:209], v[114:115], v[116:117]
	v_pk_add_f32 v[208:209], v[118:119], v[208:209]
	v_cvt_pk_f16_f32 v160, v114, v115
	v_cvt_pk_f16_f32 v161, v116, v117
	ds_read_b64_tr_b16 v[62:63], v192 offset:28672
	ds_read_b64_tr_b16 v[64:65], v192 offset:29184
	v_pk_add_f32 v[208:209], v[120:121], v[208:209]
	v_pk_add_f32 v[208:209], v[122:123], v[208:209]
	s_waitcnt lgkmcnt(10)
	v_mfma_f32_32x32x16_f16 v[66:81], v[164:167], v[144:147], v[2:17]
	v_cvt_pk_f16_f32 v162, v118, v119
	v_cvt_pk_f16_f32 v163, v120, v121
	ds_read_b64_tr_b16 v[114:115], v192 offset:25600
	ds_read_b64_tr_b16 v[116:117], v192 offset:26112
	s_waitcnt lgkmcnt(11)
	v_mfma_f32_32x32x16_f16 v[82:97], v[168:171], v[140:143], v[82:97]
	v_pk_add_f32 v[208:209], v[124:125], v[208:209]
	v_pk_add_f32 v[208:209], v[126:127], v[208:209]
	v_cvt_pk_f16_f32 v156, v122, v123
	v_cvt_pk_f16_f32 v157, v124, v125
	ds_read_b64_tr_b16 v[118:119], v192 offset:29696
	ds_read_b64_tr_b16 v[120:121], v192 offset:30208
	s_waitcnt lgkmcnt(12)
	v_mfma_f32_32x32x16_f16 v[66:81], v[172:175], v[140:143], v[66:81]
	v_pk_add_f32 v[208:209], v[128:129], v[208:209]
	v_pk_add_f32 v[208:209], v[98:99], v[208:209]
	v_cvt_pk_f16_f32 v158, v126, v127
	v_cvt_pk_f16_f32 v159, v128, v129
	ds_read_b64_tr_b16 v[122:123], v192 offset:26624
	ds_read_b64_tr_b16 v[124:125], v192 offset:27136
	s_waitcnt lgkmcnt(13)
	v_mfma_f32_32x32x16_f16 v[82:97], v[176:179], v[136:139], v[82:97]
	v_pk_add_f32 v[208:209], v[100:101], v[208:209]
	v_pk_add_f32 v[208:209], v[102:103], v[208:209]
	v_cvt_pk_f16_f32 v152, v98, v99
	v_cvt_pk_f16_f32 v153, v100, v101
	ds_read_b64_tr_b16 v[98:99], v192 offset:30720
	ds_read_b64_tr_b16 v[100:101], v192 offset:31232
	s_waitcnt lgkmcnt(14)
	v_mfma_f32_32x32x16_f16 v[66:81], v[180:183], v[136:139], v[66:81]
	v_pk_add_f32 v[208:209], v[104:105], v[208:209]
	v_pk_add_f32 v[208:209], v[106:107], v[208:209]
	v_cvt_pk_f16_f32 v154, v102, v103
	v_cvt_pk_f16_f32 v155, v104, v105
	ds_read_b64_tr_b16 v[102:103], v192 offset:27648
	ds_read_b64_tr_b16 v[104:105], v192 offset:28160
	s_waitcnt lgkmcnt(14)
	v_mfma_f32_32x32x16_f16 v[82:97], v[184:187], v[132:135], v[82:97]
	v_pk_add_f32 v[208:209], v[108:109], v[208:209]
	v_pk_add_f32 v[208:209], v[110:111], v[208:209]
	v_cvt_pk_f16_f32 v148, v106, v107
	v_cvt_pk_f16_f32 v149, v108, v109
	ds_read_b64_tr_b16 v[106:107], v192 offset:31744
	ds_read_b64_tr_b16 v[108:109], v192 offset:32256
	v_mfma_f32_32x32x16_f16 v[66:81], v[50:53], v[132:135], v[66:81]
	v_pk_add_f32 v[208:209], v[112:113], v[208:209]
	v_add_f32_e32 v50, v208, v209
	v_cvt_pk_f16_f32 v150, v110, v111
	v_cvt_pk_f16_f32 v151, v112, v113
	v_lshl_add_u64 v[52:53], v[58:59], 0, s[48:49]
	s_add_i32 s42, s25, s97
	s_mov_b32 s44, m0
	s_mov_b32 m0, s42
	s_nop 0
	global_load_lds_dwordx4 v[52:53], off
	s_mov_b32 m0, s44
	v_lshl_add_u64 v[52:53], v[60:61], 0, s[52:53]
	s_add_i32 s42, s43, s83
	s_mov_b32 s44, m0
	s_mov_b32 m0, s42
	s_nop 0
	global_load_lds_dwordx4 v[52:53], off
	s_mov_b32 m0, s44
	v_add_f32_e32 v50, v0, v50
	s_waitcnt lgkmcnt(14)
	v_mfma_f32_32x32x16_f16 v[18:33], v[160:163], v[188:191], v[18:33]
	v_exp_f32_e32 v82, v82
	v_exp_f32_e32 v83, v83
	v_exp_f32_e32 v84, v84
	v_exp_f32_e32 v85, v85
	s_waitcnt lgkmcnt(12)
	v_mfma_f32_32x32x16_f16 v[34:49], v[160:163], v[62:65], v[34:49]
	v_exp_f32_e32 v86, v86
	v_exp_f32_e32 v87, v87
	v_exp_f32_e32 v88, v88
	v_exp_f32_e32 v89, v89
	v_add_u32_e32 v0, s43, v219
	ds_read_b128 v[192:195], v0
	ds_read_b128 v[188:191], v0 offset:512
	s_waitcnt lgkmcnt(12)
	v_mfma_f32_32x32x16_f16 v[18:33], v[156:159], v[114:117], v[18:33]
	v_exp_f32_e32 v90, v90
	v_exp_f32_e32 v91, v91
	v_exp_f32_e32 v92, v92
	v_exp_f32_e32 v93, v93
	ds_read_b128 v[184:187], v0 offset:2048
	ds_read_b128 v[180:183], v0 offset:2560
	s_waitcnt lgkmcnt(12)
	v_mfma_f32_32x32x16_f16 v[34:49], v[156:159], v[118:121], v[34:49]
	v_exp_f32_e32 v94, v94
	v_exp_f32_e32 v95, v95
	v_exp_f32_e32 v96, v96
	v_exp_f32_e32 v97, v97
	ds_read_b128 v[176:179], v0 offset:4096
	ds_read_b128 v[172:175], v0 offset:4608
	s_waitcnt lgkmcnt(12)
	v_mfma_f32_32x32x16_f16 v[18:33], v[152:155], v[122:125], v[18:33]
	v_exp_f32_e32 v66, v66
	v_exp_f32_e32 v67, v67
	v_exp_f32_e32 v68, v68
	v_exp_f32_e32 v69, v69
	ds_read_b128 v[168:171], v0 offset:6144
	ds_read_b128 v[164:167], v0 offset:6656
	s_waitcnt lgkmcnt(12)
	v_mfma_f32_32x32x16_f16 v[34:49], v[152:155], v[98:101], v[34:49]
	v_exp_f32_e32 v70, v70
	v_exp_f32_e32 v71, v71
	v_exp_f32_e32 v72, v72
	v_exp_f32_e32 v73, v73
	s_waitcnt lgkmcnt(10)
	v_mfma_f32_32x32x16_f16 v[18:33], v[148:151], v[102:105], v[18:33]
	v_exp_f32_e32 v74, v74
	v_exp_f32_e32 v75, v75
	v_exp_f32_e32 v76, v76
	v_exp_f32_e32 v77, v77
	s_waitcnt lgkmcnt(8)
	v_mfma_f32_32x32x16_f16 v[34:49], v[148:151], v[106:109], v[34:49]
	v_exp_f32_e32 v78, v78
	v_exp_f32_e32 v79, v79
	v_exp_f32_e32 v80, v80
	v_exp_f32_e32 v81, v81
	s_add_i32 s45, s43, 0x2000
	s_waitcnt vmcnt(2) lgkmcnt(8)
	s_barrier
	s_cmpk_lg_i32 s43, 0x4000
	s_mov_b32 s44, s25
	s_cselect_b32 s25, s45, 0
	s_add_i32 s24, s24, 2
	v_lshl_add_u64 v[54:55], v[54:55], 0, s[62:63]
	v_lshl_add_u64 v[56:57], v[56:57], 0, s[62:63]
	s_mov_b32 s42, s43
	s_cmp_lt_u32 s24, 29
	s_cbranch_scc1 .LBB0_77
	s_mov_b64 s[36:37], 0x10c84000
	s_mov_b64 s[60:61], 0x10388000
	s_mov_b32 s45, 31
	s_branch .LBB0_80
